# attention K/V address updates: 64-bit v_lshl_add_u64 replaced by add/addc pairs on separate carry SGPRs
# speedup vs baseline: 1.0019x; 1.0019x over previous
; template <int DK, bool MLA>
; DI void attn_item(const h16* __restrict__ Q, const h16* __restrict__ Kp, const h16* __restrict__ Kr, const h16* __restrict__ Vt,
;                   int kbeg, int kend, h16* __restrict__ out, h16* sm) {
;     ...
; #pragma unroll
;     for (int i = 0; i < NCH; ++i) {
;       const int c = tid + 256 * i, key = c / NKC, part = c % NKC;
;       *(u32x4*)(ksm + key * KS + part * 8) = RK[i];
;     }
; #pragma unroll
;     for (int i = 0; i < 2; ++i) {
;       const int c = tid + 256 * i, dv = c >> 3, kc = c & 7;
;       *(u32x4*)(vsm + dv * 72 + kc * 8) = RV[i];
;     }
;     __syncthreads();
;     if (it + 2 < ntile) ATT_GLOAD(RK, RV, kbeg + (it + 2) * 64)
.LBB0_2735:
	s_add_i32 s38, s9, -1
	s_cmp_ge_u32 s38, s8
	s_waitcnt vmcnt(0)
	ds_write_b128 v129, v[124:127]
	ds_write_b128 v131, v[120:123]
	ds_write_b128 v140, v[116:119] offset:9216
	ds_write_b128 v142, v[112:115] offset:9216
	s_waitcnt lgkmcnt(0)
	s_barrier
	s_cbranch_scc1 .LBB0_2737
	s_sub_i32 s40, s6, 64
	s_lshl_b32 s40, s40, 1
	s_mov_b32 s41, 0
	global_load_dwordx4 v[124:127], v[220:221], off
	global_load_dwordx4 v[120:123], v[222:223], off
	v_add_co_u32_e64 v2, s[54:55], s40, v138
	v_add_co_u32_e64 v4, s[56:57], s40, v136
	v_add_co_u32_e64 v220, s[58:59], v220, v228
	v_add_co_u32_e64 v222, s[60:61], v222, v228
	v_addc_co_u32_e64 v3, s[54:55], 0, v139, s[54:55]
	v_addc_co_u32_e64 v5, s[56:57], 0, v137, s[56:57]
	v_addc_co_u32_e64 v221, s[58:59], 0, v221, s[58:59]
	v_addc_co_u32_e64 v223, s[60:61], 0, v223, s[60:61]
	global_load_dwordx4 v[116:119], v[2:3], off
	global_load_dwordx4 v[112:115], v[4:5], off

; #define MFMA(a, b, c) __builtin_amdgcn_mfma_f32_32x32x16_f16((a), (b), (c), 0, 0, 0)
; template <int DK, bool MLA>
; DI void attn_item(const h16* __restrict__ Q, const h16* __restrict__ Kp, const h16* __restrict__ Kr, const h16* __restrict__ Vt,
;                   int kbeg, int kend, h16* __restrict__ out, h16* sm) {
;     ...
; #pragma unroll
;     for (int i = 0; i < NCH; ++i) {
;       const int c = tid + 256 * i, key = c / NKC, part = c % NKC;
;       *(u32x4*)(ksm + key * KS + part * 8) = RK[i];
;     }
; #pragma unroll
;     for (int i = 0; i < 2; ++i) {
;       const int c = tid + 256 * i, dv = c >> 3, kc = c & 7;
;       *(u32x4*)(vsm + dv * 72 + kc * 8) = RV[i];
;     }
;     __syncthreads();
;     if (it + 2 < ntile) ATT_GLOAD(RK, RV, kbeg + (it + 2) * 64)
;     ...
;     float ps = 0.f;
; #pragma unroll
;     for (int i = 0; i < 16; ++i) {
;       st[0][i] = __builtin_amdgcn_exp2f(st[0][i]);
;       st[1][i] = __builtin_amdgcn_exp2f(st[1][i]);
;       ps += st[0][i] + st[1][i];
;     }
;     lsum += ps;
; #pragma unroll
;     for (int s4 = 0; s4 < 4; ++s4) {
;       const int kt2 = s4 >> 1, hf = s4 & 1;
;       h16x8 pb;
; #pragma unroll
;       for (int j = 0; j < 8; ++j) pb[j] = (h16)st[kt2][8 * hf + j];
;       const int kb = kt2 * 32 + 16 * hf;
; #pragma unroll
;       for (int dt = 0; dt < 2; ++dt) {
;         const h16* vp = vsm + (dt * 32 + r) * 72 + kb + 4 * hh;
;         h16x4 lo = *(const h16x4*)vp, hi = *(const h16x4*)(vp + 8);
;         h16x8 va = __builtin_shufflevector(lo, hi, 0, 1, 2, 3, 4, 5, 6, 7);
;         ot[dt] = MFMA(va, pb, ot[dt]);
;       }
;     }
.LBB0_2739:
	v_exp_f32_e32 v166, v64
	v_exp_f32_e32 v13, v65
	v_exp_f32_e32 v15, v66
	v_exp_f32_e32 v152, v67
	v_exp_f32_e32 v156, v68
	v_exp_f32_e32 v157, v69
	v_exp_f32_e32 v168, v70
	v_exp_f32_e32 v160, v71
	v_exp_f32_e32 v12, v60
	v_add_u32_e32 v60, 0x2000, v143
	v_exp_f32_e32 v158, v52
	v_exp_f32_e32 v159, v53
	v_exp_f32_e32 v169, v54
	v_exp_f32_e32 v163, v55
	v_exp_f32_e32 v164, v56
	v_exp_f32_e32 v165, v57
	v_exp_f32_e32 v10, v58
	v_exp_f32_e32 v11, v59
	ds_read_b128 v[52:55], v60 offset:1024
	ds_read_b128 v[56:59], v60 offset:1056
	v_exp_f32_e32 v167, v48
	v_exp_f32_e32 v14, v49
	v_exp_f32_e32 v154, v50
	v_exp_f32_e32 v155, v51
	v_exp_f32_e32 v4, v61
	v_cvt_pk_f16_f32 v51, v168, v160
	v_cvt_pk_f16_f32 v50, v156, v157
	v_cvt_pk_f16_f32 v49, v15, v152
	v_cvt_pk_f16_f32 v48, v166, v13
	v_add_u32_e32 v61, 0x3000, v143
	v_exp_f32_e32 v161, v72
	s_waitcnt lgkmcnt(1)
	v_mfma_f32_32x32x16_f16 v[32:47], v[52:55], v[48:51], v[32:47]
	ds_read_b128 v[52:55], v61 offset:1536
	v_exp_f32_e32 v162, v73
	v_exp_f32_e32 v7, v74
	v_exp_f32_e32 v8, v75
	v_exp_f32_e32 v9, v76
	v_exp_f32_e32 v0, v77
	v_exp_f32_e32 v2, v78
	s_waitcnt lgkmcnt(0)
	v_mfma_f32_32x32x16_f16 v[16:31], v[52:55], v[48:51], v[16:31]
	ds_read_b128 v[52:55], v61 offset:1568
	v_exp_f32_e32 v3, v79
	v_cvt_pk_f16_f32 v50, v9, v0
	v_cvt_pk_f16_f32 v49, v7, v8
	v_cvt_pk_f16_f32 v48, v161, v162
	v_cvt_pk_f16_f32 v51, v2, v3
	v_exp_f32_e32 v5, v62
	v_exp_f32_e32 v6, v63
	s_waitcnt lgkmcnt(0)
	v_mfma_f32_32x32x16_f16 v[16:31], v[52:55], v[48:51], v[16:31]
	ds_read_b128 v[52:55], v60 offset:1088
	s_cmp_ge_u32 s9, s8
	v_mfma_f32_32x32x16_f16 v[32:47], v[56:59], v[48:51], v[32:47]
	v_cvt_pk_f16_f32 v51, v169, v163
	v_cvt_pk_f16_f32 v50, v158, v159
	v_cvt_pk_f16_f32 v49, v154, v155
	v_cvt_pk_f16_f32 v48, v167, v14
	s_waitcnt lgkmcnt(0)
	s_nop 0
	v_mfma_f32_32x32x16_f16 v[32:47], v[52:55], v[48:51], v[32:47]
	ds_read_b128 v[52:55], v61 offset:1600
	s_waitcnt lgkmcnt(0)
	v_mfma_f32_32x32x16_f16 v[16:31], v[52:55], v[48:51], v[16:31]
	ds_read_b128 v[52:55], v60 offset:1120
	v_cvt_pk_f16_f32 v51, v5, v6
	v_cvt_pk_f16_f32 v50, v12, v4
	v_cvt_pk_f16_f32 v49, v10, v11
	v_cvt_pk_f16_f32 v48, v164, v165
	s_waitcnt lgkmcnt(0)
	s_nop 0
	v_mfma_f32_32x32x16_f16 v[32:47], v[52:55], v[48:51], v[32:47]
	ds_read_b128 v[52:55], v61 offset:1632
	ds_write_b128 v129, v[100:103] offset:18432
	ds_write_b128 v131, v[96:99] offset:18432
	ds_write_b128 v140, v[108:111] offset:27648
	ds_write_b128 v142, v[104:107] offset:27648
	s_waitcnt lgkmcnt(0)
	s_barrier
	v_mfma_f32_32x32x16_f16 v[16:31], v[52:55], v[48:51], v[16:31]
	s_cbranch_scc1 .LBB0_2741
	s_ashr_i32 s7, s6, 31
	s_lshl_b32 s40, s6, 1
	s_mov_b32 s41, 0
	global_load_dwordx4 v[100:103], v[220:221], off
	global_load_dwordx4 v[96:99], v[222:223], off
	v_add_co_u32_e64 v48, s[54:55], s40, v134
	v_add_co_u32_e64 v50, s[56:57], s40, v132
	v_add_co_u32_e64 v220, s[58:59], v220, v228
	v_add_co_u32_e64 v222, s[60:61], v222, v228
	v_addc_co_u32_e64 v49, s[54:55], 0, v135, s[54:55]
	v_addc_co_u32_e64 v51, s[56:57], 0, v133, s[56:57]
	v_addc_co_u32_e64 v221, s[58:59], 0, v221, s[58:59]
	v_addc_co_u32_e64 v223, s[60:61], 0, v223, s[60:61]
	global_load_dwordx4 v[108:111], v[48:49], off
	global_load_dwordx4 v[104:107], v[50:51], off

; template <int DK, bool MLA>
; DI void attn_item(const h16* __restrict__ Q, const h16* __restrict__ Kp, const h16* __restrict__ Kr, const h16* __restrict__ Vt,
;                   int kbeg, int kend, h16* __restrict__ out, h16* sm) {
;     ...
; #pragma unroll
;     for (int i = 0; i < NCH; ++i) {
;       const int c = tid + 256 * i, key = c / NKC, part = c % NKC;
;       *(u32x4*)(ksm + key * KS + part * 8) = RK[i];
;     }
; #pragma unroll
;     for (int i = 0; i < 2; ++i) {
;       const int c = tid + 256 * i, dv = c >> 3, kc = c & 7;
;       *(u32x4*)(vsm + dv * 72 + kc * 8) = RV[i];
;     }
;     __syncthreads();
;     if (it + 2 < ntile) ATT_GLOAD(RK, RV, kbeg + (it + 2) * 64)
.LBB0_2771:
	s_add_i32 s10, s9, -1
	s_cmp_ge_u32 s10, s8
	s_waitcnt vmcnt(9)
	ds_write_b128 v147, v[104:107]
	s_waitcnt vmcnt(8)
	ds_write_b128 v149, v[108:111]
	s_waitcnt vmcnt(7)
	ds_write_b128 v151, v[112:115]
	s_waitcnt vmcnt(6)
	ds_write_b128 v162, v[116:119] offset:13312
	s_waitcnt vmcnt(5)
	ds_write_b128 v164, v[120:123] offset:13312
	s_waitcnt lgkmcnt(0)
	s_barrier
	s_cbranch_scc1 .LBB0_2773
	s_sub_i32 s26, s6, 64
	s_lshl_b32 s26, s26, 1
	s_mov_b32 s27, 0
	global_load_dwordx4 v[104:107], v[220:221], off
	global_load_dwordx4 v[108:111], v[222:223], off
	global_load_dwordx4 v[112:115], v[226:227], off
	v_add_co_u32_e64 v2, s[54:55], s26, v160
	v_add_co_u32_e64 v4, s[56:57], s26, v158
	v_add_co_u32_e64 v220, s[58:59], v220, v228
	v_add_co_u32_e64 v222, s[60:61], v222, v230
	v_add_co_u32_e64 v226, s[62:63], v226, v232
	v_addc_co_u32_e64 v3, s[54:55], 0, v161, s[54:55]
	v_addc_co_u32_e64 v5, s[56:57], 0, v159, s[56:57]
	v_addc_co_u32_e64 v221, s[58:59], 0, v221, s[58:59]
	v_addc_co_u32_e64 v223, s[60:61], 0, v223, s[60:61]
	v_addc_co_u32_e64 v227, s[62:63], 0, v227, s[62:63]
	global_load_dwordx4 v[116:119], v[2:3], off
	global_load_dwordx4 v[120:123], v[4:5], off

; #define MFMA(a, b, c) __builtin_amdgcn_mfma_f32_32x32x16_f16((a), (b), (c), 0, 0, 0)
; template <int DK, bool MLA>
; DI void attn_item(const h16* __restrict__ Q, const h16* __restrict__ Kp, const h16* __restrict__ Kr, const h16* __restrict__ Vt,
;                   int kbeg, int kend, h16* __restrict__ out, h16* sm) {
;     ...
; #pragma unroll
;     for (int i = 0; i < NCH; ++i) {
;       const int c = tid + 256 * i, key = c / NKC, part = c % NKC;
;       *(u32x4*)(ksm + key * KS + part * 8) = RK[i];
;     }
; #pragma unroll
;     for (int i = 0; i < 2; ++i) {
;       const int c = tid + 256 * i, dv = c >> 3, kc = c & 7;
;       *(u32x4*)(vsm + dv * 72 + kc * 8) = RV[i];
;     }
;     __syncthreads();
;     if (it + 2 < ntile) ATT_GLOAD(RK, RV, kbeg + (it + 2) * 64)
;     ...
;     float ps = 0.f;
; #pragma unroll
;     for (int i = 0; i < 16; ++i) {
;       st[0][i] = __builtin_amdgcn_exp2f(st[0][i]);
;       st[1][i] = __builtin_amdgcn_exp2f(st[1][i]);
;       ps += st[0][i] + st[1][i];
;     }
;     lsum += ps;
; #pragma unroll
;     for (int s4 = 0; s4 < 4; ++s4) {
;       const int kt2 = s4 >> 1, hf = s4 & 1;
;       h16x8 pb;
; #pragma unroll
;       for (int j = 0; j < 8; ++j) pb[j] = (h16)st[kt2][8 * hf + j];
;       const int kb = kt2 * 32 + 16 * hf;
; #pragma unroll
;       for (int dt = 0; dt < 2; ++dt) {
;         const h16* vp = vsm + (dt * 32 + r) * 72 + kb + 4 * hh;
;         h16x4 lo = *(const h16x4*)vp, hi = *(const h16x4*)(vp + 8);
;         h16x8 va = __builtin_shufflevector(lo, hi, 0, 1, 2, 3, 4, 5, 6, 7);
;         ot[dt] = MFMA(va, pb, ot[dt]);
;       }
;     }
.LBB0_2775:
	v_exp_f32_e32 v192, v64
	v_exp_f32_e32 v193, v65
	v_exp_f32_e32 v5, v66
	v_exp_f32_e32 v6, v67
	v_exp_f32_e32 v186, v68
	v_exp_f32_e32 v9, v69
	v_exp_f32_e32 v188, v70
	v_exp_f32_e32 v189, v71
	v_exp_f32_e32 v15, v60
	v_add_u32_e32 v60, 0x3000, v165
	v_exp_f32_e32 v187, v52
	v_exp_f32_e32 v13, v53
	v_exp_f32_e32 v190, v54
	v_exp_f32_e32 v191, v55
	v_exp_f32_e32 v183, v56
	v_exp_f32_e32 v184, v57
	v_exp_f32_e32 v185, v58
	v_exp_f32_e32 v14, v59
	ds_read_b128 v[52:55], v60 offset:1024
	ds_read_b128 v[56:59], v60 offset:1056
	v_exp_f32_e32 v194, v48
	v_exp_f32_e32 v195, v49
	v_exp_f32_e32 v7, v50
	v_exp_f32_e32 v8, v51
	v_exp_f32_e32 v179, v61
	v_cvt_pk_f16_f32 v51, v188, v189
	v_cvt_pk_f16_f32 v50, v186, v9
	v_cvt_pk_f16_f32 v49, v5, v6
	v_cvt_pk_f16_f32 v48, v192, v193
	v_add_u32_e32 v61, 0x4000, v165
	v_exp_f32_e32 v180, v72
	s_waitcnt lgkmcnt(1)
	v_mfma_f32_32x32x16_f16 v[32:47], v[52:55], v[48:51], v[32:47]
	ds_read_b128 v[52:55], v61 offset:1536
	v_exp_f32_e32 v181, v73
	v_exp_f32_e32 v182, v74
	v_exp_f32_e32 v10, v75
	v_exp_f32_e32 v11, v76
	v_exp_f32_e32 v12, v77
	v_exp_f32_e32 v0, v78
	s_waitcnt lgkmcnt(0)
	v_mfma_f32_32x32x16_f16 v[16:31], v[52:55], v[48:51], v[16:31]
	ds_read_b128 v[52:55], v61 offset:1568
	v_exp_f32_e32 v2, v79
	v_cvt_pk_f16_f32 v50, v11, v12
	v_cvt_pk_f16_f32 v49, v182, v10
	v_cvt_pk_f16_f32 v48, v180, v181
	v_cvt_pk_f16_f32 v51, v0, v2
	v_exp_f32_e32 v3, v62
	v_exp_f32_e32 v4, v63
	s_waitcnt lgkmcnt(0)
	v_mfma_f32_32x32x16_f16 v[16:31], v[52:55], v[48:51], v[16:31]
	ds_read_b128 v[52:55], v60 offset:1088
	s_cmp_ge_u32 s9, s8
	v_mfma_f32_32x32x16_f16 v[32:47], v[56:59], v[48:51], v[32:47]
	v_cvt_pk_f16_f32 v51, v190, v191
	v_cvt_pk_f16_f32 v50, v187, v13
	v_cvt_pk_f16_f32 v49, v7, v8
	v_cvt_pk_f16_f32 v48, v194, v195
	s_waitcnt lgkmcnt(0)
	s_nop 0
	v_mfma_f32_32x32x16_f16 v[32:47], v[52:55], v[48:51], v[32:47]
	ds_read_b128 v[52:55], v61 offset:1600
	s_waitcnt lgkmcnt(0)
	v_mfma_f32_32x32x16_f16 v[16:31], v[52:55], v[48:51], v[16:31]
	ds_read_b128 v[52:55], v60 offset:1120
	v_cvt_pk_f16_f32 v51, v3, v4
	v_cvt_pk_f16_f32 v50, v15, v179
	v_cvt_pk_f16_f32 v49, v185, v14
	v_cvt_pk_f16_f32 v48, v183, v184
	s_waitcnt lgkmcnt(0)
	s_nop 0
	v_mfma_f32_32x32x16_f16 v[32:47], v[52:55], v[48:51], v[32:47]
	ds_read_b128 v[52:55], v61 offset:1632
	s_waitcnt vmcnt(4)
	ds_write_b128 v147, v[124:127] offset:22528
	s_waitcnt vmcnt(3)
	ds_write_b128 v149, v[128:131] offset:22528
	s_waitcnt vmcnt(2)
	ds_write_b128 v151, v[132:135] offset:22528
	s_waitcnt vmcnt(0)
	ds_write_b128 v162, v[140:143] offset:35840
	ds_write_b128 v164, v[136:139] offset:35840
	s_waitcnt lgkmcnt(0)
	s_barrier
	v_mfma_f32_32x32x16_f16 v[16:31], v[52:55], v[48:51], v[16:31]
	s_cbranch_scc1 .LBB0_2777
	s_ashr_i32 s7, s6, 31
	s_lshl_b32 s26, s6, 1
	s_mov_b32 s27, 0
	global_load_dwordx4 v[124:127], v[220:221], off
	global_load_dwordx4 v[128:131], v[222:223], off
	global_load_dwordx4 v[132:135], v[226:227], off
	v_add_co_u32_e64 v48, s[54:55], s26, v154
	v_add_co_u32_e64 v50, s[56:57], s26, v156
	v_add_co_u32_e64 v220, s[58:59], v220, v228
	v_add_co_u32_e64 v222, s[60:61], v222, v230
	v_add_co_u32_e64 v226, s[62:63], v226, v232
	v_addc_co_u32_e64 v49, s[54:55], 0, v155, s[54:55]
	v_addc_co_u32_e64 v51, s[56:57], 0, v157, s[56:57]
	v_addc_co_u32_e64 v221, s[58:59], 0, v221, s[58:59]
	v_addc_co_u32_e64 v223, s[60:61], 0, v223, s[60:61]
	v_addc_co_u32_e64 v227, s[62:63], 0, v227, s[62:63]
	global_load_dwordx4 v[140:143], v[48:49], off
	global_load_dwordx4 v[136:139], v[50:51], off
